# waves 1-7 touch the next phase's code with global loads at every phase seam (L2 warm-up of the instruction stream)
# baseline (speedup 1.0000x reference)
.LBB0_161:
	s_or_b64 exec, exec, s[18:19]
	s_cmp_lt_i32 s51, 3
	s_cbranch_scc1 .LBB0_215
	s_waitcnt vmcnt(0)
	s_barrier
	v_readfirstlane_b32 s100, v0
	s_nop 3
	s_cmp_lt_u32 s100, 64
	s_cbranch_scc1 .Lpf214_skip
	s_getpc_b64 s[100:101]
.Lpf214_pc:
	s_add_u32 s100, s100, (.LBB0_219-.Lpf214_pc)&4294967295
	s_addc_u32 s101, s101, (.LBB0_219-.Lpf214_pc)>>32
	v_lshlrev_b32_e32 v16, 4, v0
	v_add_u32_e32 v16, 0xfffffc00, v16
	global_load_dwordx4 v[20:23], v16, s[100:101]
	s_add_u32 s100, s100, 0x1c00
	s_addc_u32 s101, s101, 0
	global_load_dwordx4 v[24:27], v16, s[100:101]
	s_add_u32 s100, s100, 0x1c00
	s_addc_u32 s101, s101, 0
	global_load_dwordx4 v[28:31], v16, s[100:101]
.Lpf214_skip:
	s_mov_b64 s[4:5], exec
	v_readlane_b32 s0, v253, 0
	v_readlane_b32 s1, v253, 1
	s_and_b64 s[0:1], s[4:5], s[0:1]
	s_mov_b64 exec, s[0:1]
	s_cbranch_execz .LBB0_214
	s_waitcnt lgkmcnt(0)
	v_mov_b32_e32 v2, 0x20160
	ds_read2_b32 v[4:5], v2 offset1:1
	ds_read_b32 v6, v2 offset:8
	v_readlane_b32 s100, v254, 8
	v_readlane_b32 s101, v254, 9
	v_mov_b32_e32 v3, 1
	v_mov_b32_e32 v11, 0
	v_mov_b32_e32 v8, s100
	v_mov_b32_e32 v9, s101
	global_atomic_add v10, v[8:9], v3, off sc0
	s_waitcnt lgkmcnt(0)
	v_add_u32_e32 v7, 1, v6
	ds_write_b32 v2, v7 offset:8
	v_mul_lo_u32 v4, v4, v7
	v_mul_lo_u32 v5, v5, v7
	s_waitcnt vmcnt(0)
	buffer_inv sc1
	v_add_u32_e32 v10, 1, v10
	v_cmp_eq_u32_e32 vcc, v10, v4
	s_cbranch_vccz .Lxb2_follow
	buffer_wbl2 sc1
	v_readlane_b32 s100, v254, 12
	v_readlane_b32 s101, v254, 13
	s_nop 1
	v_mov_b32_e32 v8, s100
	v_mov_b32_e32 v9, s101
	s_waitcnt vmcnt(0)
	global_atomic_add v10, v[8:9], v3, off sc0
	v_readlane_b32 s100, v254, 10
	v_readlane_b32 s101, v254, 11
	s_nop 1
	v_mov_b32_e32 v12, s100
	v_mov_b32_e32 v13, s101
	v_readlane_b32 s100, v254, 14
	v_readlane_b32 s101, v254, 15
	s_nop 1
	v_mov_b32_e32 v8, s100
	v_mov_b32_e32 v9, s101
	s_waitcnt vmcnt(0)
	v_add_u32_e32 v10, 1, v10
	v_cmp_eq_u32_e32 vcc, v10, v5
	s_cbranch_vccz .Lxb2_topwait
	global_atomic_add v[12:13], v3, off
	global_atomic_add v[8:9], v3, off
	s_branch .Lxb2_fin

.LBB0_214:
	s_or_b64 exec, exec, s[4:5]
	s_waitcnt vmcnt(0)
	s_waitcnt lgkmcnt(0)
	s_barrier

.LBB0_235:
	s_add_i32 s7, s17, 3
	s_cmp_ge_i32 s7, s51
	s_cbranch_scc1 .LBB0_289
	s_waitcnt vmcnt(0)
	s_waitcnt lgkmcnt(0)
	s_barrier
	v_readfirstlane_b32 s100, v0
	s_nop 3
	s_cmp_lt_u32 s100, 64
	s_cbranch_scc1 .Lpf288_skip
	s_getpc_b64 s[100:101]
.Lpf288_pc:
	s_add_u32 s100, s100, (.LBB0_289-.Lpf288_pc)&4294967295
	s_addc_u32 s101, s101, (.LBB0_289-.Lpf288_pc)>>32
	v_lshlrev_b32_e32 v16, 4, v0
	v_add_u32_e32 v16, 0xfffffc00, v16
	global_load_dwordx4 v[20:23], v16, s[100:101]
	s_add_u32 s100, s100, 0x1c00
	s_addc_u32 s101, s101, 0
	global_load_dwordx4 v[24:27], v16, s[100:101]
.Lpf288_skip:
	s_mov_b64 s[4:5], exec
	v_readlane_b32 s8, v253, 0
	v_readlane_b32 s9, v253, 1
	s_and_b64 s[8:9], s[4:5], s[8:9]
	s_mov_b64 exec, s[8:9]
	s_cbranch_execz .LBB0_288
	s_waitcnt lgkmcnt(0)
	v_mov_b32_e32 v2, 0x20160
	ds_read2_b32 v[4:5], v2 offset1:1
	ds_read_b32 v6, v2 offset:8
	v_readlane_b32 s100, v254, 8
	v_readlane_b32 s101, v254, 9
	v_mov_b32_e32 v3, 1
	v_mov_b32_e32 v11, 0
	v_mov_b32_e32 v8, s100
	v_mov_b32_e32 v9, s101
	global_atomic_add v10, v[8:9], v3, off sc0
	s_waitcnt lgkmcnt(0)
	v_add_u32_e32 v7, 1, v6
	ds_write_b32 v2, v7 offset:8
	v_mul_lo_u32 v4, v4, v7
	v_mul_lo_u32 v5, v5, v7
	s_waitcnt vmcnt(0)
	buffer_inv sc1
	v_add_u32_e32 v10, 1, v10
	v_cmp_eq_u32_e32 vcc, v10, v4
	s_cbranch_vccz .Lxb3_follow
	buffer_wbl2 sc1
	v_readlane_b32 s100, v254, 12
	v_readlane_b32 s101, v254, 13
	s_nop 1
	v_mov_b32_e32 v8, s100
	v_mov_b32_e32 v9, s101
	s_waitcnt vmcnt(0)
	global_atomic_add v10, v[8:9], v3, off sc0
	v_readlane_b32 s100, v254, 10
	v_readlane_b32 s101, v254, 11
	s_nop 1
	v_mov_b32_e32 v12, s100
	v_mov_b32_e32 v13, s101
	v_readlane_b32 s100, v254, 14
	v_readlane_b32 s101, v254, 15
	s_nop 1
	v_mov_b32_e32 v8, s100
	v_mov_b32_e32 v9, s101
	s_waitcnt vmcnt(0)
	v_add_u32_e32 v10, 1, v10
	v_cmp_eq_u32_e32 vcc, v10, v5
	s_cbranch_vccz .Lxb3_topwait
	global_atomic_add v[12:13], v3, off
	global_atomic_add v[8:9], v3, off
	s_branch .Lxb3_fin

.LBB0_308:
	s_add_i32 s7, s17, 4
	s_cmp_ge_i32 s7, s51
	s_cbranch_scc1 .LBB0_362
	s_waitcnt vmcnt(0)
	s_waitcnt vmcnt(0) lgkmcnt(0)
	s_barrier
	v_readfirstlane_b32 s100, v0
	s_nop 3
	s_cmp_lt_u32 s100, 64
	s_cbranch_scc1 .Lpf361_skip
	s_getpc_b64 s[100:101]

.LBB0_388:
	s_add_i32 s6, s17, 5
	s_cmp_ge_i32 s6, s51
	s_cbranch_scc1 .LBB0_442
	s_waitcnt vmcnt(0)
	s_waitcnt vmcnt(0)
	s_barrier
	v_readfirstlane_b32 s100, v0
	s_nop 3
	s_cmp_lt_u32 s100, 64
	s_cbranch_scc1 .Lpf441_skip
	s_getpc_b64 s[100:101]
.Lpf441_pc:
	s_add_u32 s100, s100, (.LBB0_442-.Lpf441_pc)&4294967295
	s_addc_u32 s101, s101, (.LBB0_442-.Lpf441_pc)>>32
	v_lshlrev_b32_e32 v16, 4, v0
	v_add_u32_e32 v16, 0xfffffc00, v16
	global_load_dwordx4 v[20:23], v16, s[100:101]
	s_add_u32 s100, s100, 0x1c00
	s_addc_u32 s101, s101, 0
	global_load_dwordx4 v[24:27], v16, s[100:101]
	s_add_u32 s100, s100, 0x1c00
	s_addc_u32 s101, s101, 0
	global_load_dwordx4 v[28:31], v16, s[100:101]
	s_add_u32 s100, s100, 0x1c00
	s_addc_u32 s101, s101, 0
	global_load_dwordx4 v[32:35], v16, s[100:101]

.LBB0_495:
	s_add_i32 s6, s17, 6
	s_cmp_ge_i32 s6, s51
	s_cbranch_scc1 .LBB0_549
	s_waitcnt vmcnt(0)
	s_waitcnt vmcnt(0)
	s_barrier
	v_readfirstlane_b32 s100, v0
	s_nop 3
	s_cmp_lt_u32 s100, 64
	s_cbranch_scc1 .Lpf548_skip
	s_getpc_b64 s[100:101]
.Lpf548_pc:
	s_add_u32 s100, s100, (.LBB0_549-.Lpf548_pc)&4294967295
	s_addc_u32 s101, s101, (.LBB0_549-.Lpf548_pc)>>32
	v_lshlrev_b32_e32 v16, 4, v0
	v_add_u32_e32 v16, 0xfffffc00, v16
	global_load_dwordx4 v[20:23], v16, s[100:101]
	s_add_u32 s100, s100, 0x1c00
	s_addc_u32 s101, s101, 0
	global_load_dwordx4 v[24:27], v16, s[100:101]
	s_add_u32 s100, s100, 0x1c00
	s_addc_u32 s101, s101, 0
	global_load_dwordx4 v[28:31], v16, s[100:101]
	s_add_u32 s100, s100, 0x1c00
	s_addc_u32 s101, s101, 0
	global_load_dwordx4 v[32:35], v16, s[100:101]
	s_add_u32 s100, s100, 0x1c00
	s_addc_u32 s101, s101, 0
	global_load_dwordx4 v[36:39], v16, s[100:101]

.LBB0_627:
	s_add_i32 s6, s17, 7
	s_cmp_ge_i32 s6, s51
	s_cbranch_scc1 .LBB0_681
	s_waitcnt vmcnt(0)
	s_waitcnt vmcnt(0)
	s_barrier
	v_readfirstlane_b32 s100, v0
	s_nop 3
	s_cmp_lt_u32 s100, 64
	s_cbranch_scc1 .Lpf680_skip
	s_getpc_b64 s[100:101]

.LBB0_842:
	s_add_i32 s6, s17, 8
	s_cmp_ge_i32 s6, s51
	s_cbranch_scc1 .LBB0_896
	s_waitcnt vmcnt(0)
	s_waitcnt vmcnt(0) lgkmcnt(0)
	s_barrier
	v_readfirstlane_b32 s100, v0
	s_nop 3
	s_cmp_lt_u32 s100, 64
	s_cbranch_scc1 .Lpf895_skip
	s_getpc_b64 s[100:101]

.LBB0_908:
	s_add_i32 s7, s17, 9
	s_cmp_ge_i32 s7, s51
	s_cbranch_scc1 .LBB0_962
	s_waitcnt vmcnt(0)
	s_waitcnt vmcnt(0) lgkmcnt(0)
	s_barrier
	v_readfirstlane_b32 s100, v0
	s_nop 3
	s_cmp_lt_u32 s100, 64
	s_cbranch_scc1 .Lpf961_skip
	s_getpc_b64 s[100:101]

.LBB0_1020:
	s_add_i32 s6, s17, 10
	s_cmp_ge_i32 s6, s51
	s_cbranch_scc1 .LBB0_1074
	s_waitcnt vmcnt(0)
	s_waitcnt vmcnt(0) lgkmcnt(0)
	s_barrier
	v_readfirstlane_b32 s100, v0
	s_nop 3
	s_cmp_lt_u32 s100, 64
	s_cbranch_scc1 .Lpf1073_skip
	s_getpc_b64 s[100:101]

.LBB0_1088:
	s_or_b64 exec, exec, s[4:5]
	s_add_i32 s6, s17, 11
	s_cmp_ge_i32 s6, s51
	s_cbranch_scc1 .LBB0_1142
	s_waitcnt vmcnt(0)
	s_waitcnt vmcnt(0) lgkmcnt(0)
	s_barrier
	v_readfirstlane_b32 s100, v0
	s_nop 3
	s_cmp_lt_u32 s100, 64
	s_cbranch_scc1 .Lpf1141_skip
	s_getpc_b64 s[100:101]

.LBB0_1236:
	s_waitcnt vmcnt(0)
	s_waitcnt vmcnt(0) lgkmcnt(0)
	s_barrier
	v_readfirstlane_b32 s100, v0
	s_nop 3
	s_cmp_lt_u32 s100, 64
	s_cbranch_scc1 .Lpf217_skip
	s_getpc_b64 s[100:101]

.Lpf217_skip:
	s_mov_b64 s[4:5], exec
	v_readlane_b32 s6, v253, 0
	v_readlane_b32 s7, v253, 1
	s_and_b64 s[6:7], s[4:5], s[6:7]
	s_mov_b64 exec, s[6:7]
	s_cbranch_execnz .LBB0_1237
	s_getpc_b64 s[98:99]
